# v25 = v22 with a true stagger inside the good barrier region: waves 0-3 barrier right after the DMA issue, waves 4-7 after the 4th PV MFMA
# speedup vs baseline: 1.0025x; 1.0025x over previous
.LBB0_567:
	v_readlane_b32 s101, v246, 60
	s_add_u32 s48, s64, 0x6c000
	s_addc_u32 s49, s65, 0
	s_cmp_lg_u32 0, -1
	s_cselect_b32 s60, 0, 0
	s_waitcnt vmcnt(0) lgkmcnt(0)
	s_barrier
	s_add_i32 s60, s60, s73
	s_add_i32 s60, s60, 0x9000
	s_mov_b32 m0, s60
	s_nop 0
	global_load_lds_dwordx4 v183, s[48:49]
	s_and_saveexec_b64 s[48:49], s[2:3]
	s_cbranch_execz .LBB0_569
	s_add_u32 s60, s46, 0x3000
	s_addc_u32 s61, s47, 0
	s_add_i32 s66, s76, 0x9000
	s_mov_b32 m0, s66
	s_nop 0
	global_load_lds_dwordx4 v184, s[60:61]

.LBB0_577:
	s_cmp_lt_u32 s101, 4
	s_cbranch_scc0 .Lstg_mid1
	s_waitcnt vmcnt(3) lgkmcnt(0)
	s_barrier
.Lstg_mid1:
	ds_read_b64_tr_b16 v[40:41], v167 offset:54272
	ds_read_b64_tr_b16 v[42:43], v167 offset:54784
	s_waitcnt lgkmcnt(6)
	v_mfma_f32_32x32x16_bf16 v[16:31], v[132:135], v[32:35], v[16:31]
	v_exp_f32_e32 v80, v80
	v_exp_f32_e32 v81, v81
	v_exp_f32_e32 v82, v82
	v_exp_f32_e32 v83, v83
	ds_read_b64_tr_b16 v[32:33], v167 offset:51200
	ds_read_b64_tr_b16 v[34:35], v167 offset:51712
	s_waitcnt lgkmcnt(6)
	v_mfma_f32_32x32x16_bf16 v[0:15], v[132:135], v[48:51], v[0:15]
	v_exp_f32_e32 v84, v84
	v_exp_f32_e32 v85, v85
	v_exp_f32_e32 v86, v86
	v_exp_f32_e32 v87, v87
	ds_read_b64_tr_b16 v[44:45], v167 offset:55296
	ds_read_b64_tr_b16 v[46:47], v167 offset:55808
	s_waitcnt lgkmcnt(6)
	v_mfma_f32_32x32x16_bf16 v[16:31], v[128:131], v[36:39], v[16:31]
	v_exp_f32_e32 v88, v88
	v_exp_f32_e32 v89, v89
	v_exp_f32_e32 v90, v90
	v_exp_f32_e32 v91, v91
	ds_read_b64_tr_b16 v[48:49], v167 offset:52224
	ds_read_b64_tr_b16 v[50:51], v167 offset:52736
	s_waitcnt lgkmcnt(6)
	v_mfma_f32_32x32x16_bf16 v[0:15], v[128:131], v[40:43], v[0:15]
	s_cmp_lt_u32 s101, 4
	s_cbranch_scc1 .Lstg_b1
	s_waitcnt vmcnt(3) lgkmcnt(0)
	s_barrier
.Lstg_b1:
	v_exp_f32_e32 v92, v92
	v_exp_f32_e32 v93, v93
	v_exp_f32_e32 v94, v94
	v_exp_f32_e32 v95, v95
	ds_read_b64_tr_b16 v[40:41], v167 offset:56320
	ds_read_b64_tr_b16 v[42:43], v167 offset:56832
	s_waitcnt lgkmcnt(6)
	v_mfma_f32_32x32x16_bf16 v[16:31], v[124:127], v[32:35], v[16:31]
	v_exp_f32_e32 v64, v64
	v_exp_f32_e32 v65, v65
	v_exp_f32_e32 v66, v66
	v_exp_f32_e32 v67, v67
	v_add_u32_e32 v142, s83, v179
	ds_read_b128 v[32:35], v142
	s_waitcnt lgkmcnt(5)
	v_mfma_f32_32x32x16_bf16 v[0:15], v[124:127], v[44:47], v[0:15]
	v_exp_f32_e32 v68, v68
	v_exp_f32_e32 v69, v69
	v_exp_f32_e32 v70, v70
	v_exp_f32_e32 v71, v71
	ds_read_b128 v[36:39], v142 offset:512
	s_waitcnt lgkmcnt(4)
	v_mfma_f32_32x32x16_bf16 v[16:31], v[120:123], v[48:51], v[16:31]
	v_exp_f32_e32 v72, v72
	v_exp_f32_e32 v73, v73
	v_exp_f32_e32 v74, v74
	v_exp_f32_e32 v75, v75
	ds_read_b128 v[136:139], v142 offset:2048
	s_waitcnt lgkmcnt(3)
	v_mfma_f32_32x32x16_bf16 v[0:15], v[120:123], v[40:43], v[0:15]
	v_exp_f32_e32 v76, v76
	v_exp_f32_e32 v77, v77
	v_exp_f32_e32 v78, v78
	v_exp_f32_e32 v79, v79
	s_andn2_b64 vcc, exec, s[60:61]
	s_cbranch_vccnz .LBB0_579
	s_waitcnt lgkmcnt(0)
	v_add_u32_e32 v52, s54, v146
	ds_read_b128 v[40:43], v52 offset:96
	ds_read_b128 v[44:47], v52 offset:64
	ds_read_b128 v[48:51], v52 offset:32
	ds_read_b128 v[52:55], v52
	s_waitcnt lgkmcnt(3)
	v_pk_mul_f32 v[28:29], v[28:29], v[40:41]
	s_waitcnt lgkmcnt(2)
	v_pk_mul_f32 v[24:25], v[24:25], v[44:45]
	s_waitcnt lgkmcnt(1)
	v_pk_mul_f32 v[20:21], v[20:21], v[48:49]
	v_pk_mul_f32 v[30:31], v[30:31], v[42:43]
	v_pk_mul_f32 v[26:27], v[26:27], v[46:47]
	v_pk_mul_f32 v[22:23], v[22:23], v[50:51]
	s_waitcnt lgkmcnt(0)
	v_pk_mul_f32 v[18:19], v[18:19], v[54:55]
	v_pk_mul_f32 v[16:17], v[16:17], v[52:53]
	v_pk_mul_f32 v[12:13], v[12:13], v[40:41]
	v_pk_mul_f32 v[8:9], v[8:9], v[44:45]
	v_pk_mul_f32 v[4:5], v[4:5], v[48:49]
	v_pk_mul_f32 v[14:15], v[14:15], v[42:43]
	v_pk_mul_f32 v[10:11], v[10:11], v[46:47]
	v_pk_mul_f32 v[6:7], v[6:7], v[50:51]
	v_pk_mul_f32 v[2:3], v[2:3], v[54:55]
	v_pk_mul_f32 v[0:1], v[0:1], v[52:53]

.Lstg_mid2:
	s_add_i32 s0, s83, 0x3000
	s_cmpk_lg_u32 s83, 0x9000
	s_cselect_b32 s82, s0, 0
	ds_read_b64_tr_b16 v[72:73], v141 offset:54272
	ds_read_b64_tr_b16 v[74:75], v141 offset:54784
	s_waitcnt lgkmcnt(6)
	v_mfma_f32_32x32x16_bf16 v[16:31], v[132:135], v[64:67], v[16:31]
	v_exp_f32_e32 v48, v48
	v_exp_f32_e32 v49, v49
	v_exp_f32_e32 v50, v50
	v_exp_f32_e32 v51, v51
	ds_read_b64_tr_b16 v[64:65], v141 offset:51200
	ds_read_b64_tr_b16 v[66:67], v141 offset:51712
	s_waitcnt lgkmcnt(6)
	v_mfma_f32_32x32x16_bf16 v[0:15], v[132:135], v[80:83], v[0:15]
	v_exp_f32_e32 v52, v52
	v_exp_f32_e32 v53, v53
	v_exp_f32_e32 v54, v54
	v_exp_f32_e32 v55, v55
	s_add_i32 s0, s79, 0x2000
	s_cmpk_lg_i32 s79, 0x4000
	s_cselect_b32 s0, s0, 0xe800
	s_cmpk_lg_u32 s79, 0xe800
	s_cselect_b32 s84, s0, 0
	ds_read_b64_tr_b16 v[76:77], v141 offset:55296
	ds_read_b64_tr_b16 v[78:79], v141 offset:55808
	s_waitcnt lgkmcnt(6)
	v_mfma_f32_32x32x16_bf16 v[16:31], v[128:131], v[68:71], v[16:31]
	v_exp_f32_e32 v56, v56
	v_exp_f32_e32 v57, v57
	v_exp_f32_e32 v58, v58
	v_exp_f32_e32 v59, v59
	s_add_i32 s0, s82, 0x3000
	s_cmpk_lg_u32 s82, 0x9000
	s_cselect_b32 s85, s0, 0
	ds_read_b64_tr_b16 v[68:69], v141 offset:52224
	ds_read_b64_tr_b16 v[70:71], v141 offset:52736
	s_waitcnt lgkmcnt(6)
	v_mfma_f32_32x32x16_bf16 v[0:15], v[128:131], v[72:75], v[0:15]
	s_cmp_lt_u32 s101, 4
	s_cbranch_scc1 .Lstg_b2
	s_waitcnt vmcnt(3) lgkmcnt(0)
	s_barrier
.Lstg_b2:
	v_exp_f32_e32 v60, v60
	v_exp_f32_e32 v61, v61
	v_exp_f32_e32 v62, v62
	v_exp_f32_e32 v63, v63
	s_add_u32 s68, s68, 0x30000
	s_addc_u32 s69, s69, 0
	ds_read_b64_tr_b16 v[72:73], v141 offset:56320
	ds_read_b64_tr_b16 v[74:75], v141 offset:56832
	s_waitcnt lgkmcnt(6)
	v_mfma_f32_32x32x16_bf16 v[16:31], v[124:127], v[64:67], v[16:31]
	v_exp_f32_e32 v32, v32
	v_exp_f32_e32 v33, v33
	v_exp_f32_e32 v34, v34
	v_exp_f32_e32 v35, v35
	s_add_u32 s48, s48, 0x48000
	s_addc_u32 s49, s49, 0
	v_add_u32_e32 v64, s82, v179
	ds_read_b128 v[80:83], v64
	s_waitcnt lgkmcnt(5)
	v_mfma_f32_32x32x16_bf16 v[0:15], v[124:127], v[76:79], v[0:15]
	v_exp_f32_e32 v36, v36
	v_exp_f32_e32 v37, v37
	v_exp_f32_e32 v38, v38
	v_exp_f32_e32 v39, v39
	s_add_u32 s8, s8, 0x2000
	s_addc_u32 s9, s9, 0
	ds_read_b128 v[136:139], v64 offset:512
	s_waitcnt lgkmcnt(4)
	v_mfma_f32_32x32x16_bf16 v[16:31], v[120:123], v[68:71], v[16:31]
	v_exp_f32_e32 v40, v40
	v_exp_f32_e32 v41, v41
	v_exp_f32_e32 v42, v42
	v_exp_f32_e32 v43, v43
	s_add_i32 s0, s87, 2
	ds_read_b128 v[140:143], v64 offset:2048
	s_waitcnt lgkmcnt(3)
	v_mfma_f32_32x32x16_bf16 v[0:15], v[120:123], v[72:75], v[0:15]
	v_exp_f32_e32 v44, v44
	v_exp_f32_e32 v45, v45
	v_exp_f32_e32 v46, v46
	v_exp_f32_e32 v47, v47
	s_andn2_b64 vcc, exec, s[60:61]
	s_cbranch_vccnz .LBB0_587
	s_waitcnt lgkmcnt(0)
	v_add_u32_e32 v76, s54, v146
	ds_read_b128 v[64:67], v76 offset:96
	ds_read_b128 v[68:71], v76 offset:64
	ds_read_b128 v[72:75], v76 offset:32
	ds_read_b128 v[76:79], v76
	s_waitcnt lgkmcnt(3)
	v_pk_mul_f32 v[28:29], v[28:29], v[64:65]
	s_waitcnt lgkmcnt(2)
	v_pk_mul_f32 v[24:25], v[24:25], v[68:69]
	s_waitcnt lgkmcnt(1)
	v_pk_mul_f32 v[20:21], v[20:21], v[72:73]
	v_pk_mul_f32 v[30:31], v[30:31], v[66:67]
	v_pk_mul_f32 v[26:27], v[26:27], v[70:71]
	v_pk_mul_f32 v[22:23], v[22:23], v[74:75]
	s_waitcnt lgkmcnt(0)
	v_pk_mul_f32 v[18:19], v[18:19], v[78:79]
	v_pk_mul_f32 v[16:17], v[16:17], v[76:77]
	v_pk_mul_f32 v[12:13], v[12:13], v[64:65]
	v_pk_mul_f32 v[8:9], v[8:9], v[68:69]
	v_pk_mul_f32 v[4:5], v[4:5], v[72:73]
	v_pk_mul_f32 v[14:15], v[14:15], v[66:67]
	v_pk_mul_f32 v[10:11], v[10:11], v[70:71]
	v_pk_mul_f32 v[6:7], v[6:7], v[74:75]
	v_pk_mul_f32 v[2:3], v[2:3], v[78:79]
	v_pk_mul_f32 v[0:1], v[0:1], v[76:77]
